# P0: x->out copy streams contiguous 8KiB blocks per wave with 8 loads in flight; phase-0 seam uses the XCD barrier; EpiResid RMW pipelined 3 row-groups deep with counted vmcnt; norm partial folds batch
# baseline (speedup 1.0000x reference)
;     __device__ __forceinline__ void operator()(const pg8::f32x4 (&acc)[2][2][4][2], const pg8::Unit& uu, int wr, int wc, int fr, int fq) const {
;     ...
;         if (!((uu.pn >> 30) & 1)) {
; #pragma unroll
;             for (int ai = 0; ai < 2; ++ai)
; #pragma unroll
;                 for (int m = 0; m < 4; ++m) { float* rowp = base + (size_t)(wr * 64 + fr + ai * 128 + m * 16) * D + col0;
; #pragma unroll
;                     for (int bj = 0; bj < 2; ++bj)
; #pragma unroll
;                         for (int n = 0; n < 2; ++n) { pg8::f32x4* p = (pg8::f32x4*)(rowp + bj * 128 + 4 * n); *p = *p + gv[bj][n] * acc[ai][bj][m][n]; } }
.LBB0_72:
	v_add_u32_e32 v164, s63, v169
	v_ashrrev_i32_e32 v165, 31, v164
	v_lshl_add_u64 v[162:163], v[162:163], 2, s[40:41]
	v_lshlrev_b64 v[164:165], 12, v[164:165]
	v_lshl_add_u64 v[162:163], v[162:163], 0, v[164:165]
	s_mov_b32 s41, 0
	global_load_dwordx4 v[170:173], v[162:163], off
	global_load_dwordx4 v[174:177], v[162:163], off offset:16
	global_load_dwordx4 v[178:181], v[162:163], off offset:512
	global_load_dwordx4 v[182:185], v[162:163], off offset:528
	s_mov_b32 s40, 0x10000
	v_lshl_add_u64 v[164:165], v[162:163], 0, s[40:41]
	global_load_dwordx4 v[186:189], v[164:165], off
	global_load_dwordx4 v[192:195], v[164:165], off offset:16
	global_load_dwordx4 v[196:199], v[164:165], off offset:512
	global_load_dwordx4 v[200:203], v[164:165], off offset:528
	s_mov_b32 s40, 0x20000
	v_lshl_add_u64 v[238:239], v[162:163], 0, s[40:41]
	global_load_dwordx4 v[218:221], v[238:239], off
	global_load_dwordx4 v[222:225], v[238:239], off offset:16
	global_load_dwordx4 v[230:233], v[238:239], off offset:512
	global_load_dwordx4 v[234:237], v[238:239], off offset:528
	s_mov_b32 s40, 0x30000
	v_lshl_add_u64 v[240:241], v[162:163], 0, s[40:41]
	s_mov_b32 s40, 0x80000
	v_lshl_add_u64 v[242:243], v[162:163], 0, s[40:41]
	s_mov_b32 s40, 0x90000
	v_lshl_add_u64 v[244:245], v[162:163], 0, s[40:41]
	s_mov_b32 s40, 0xa0000
	v_lshl_add_u64 v[246:247], v[162:163], 0, s[40:41]
	s_mov_b32 s40, 0xb0000
	v_lshl_add_u64 v[248:249], v[162:163], 0, s[40:41]
	s_mov_b32 s16, 0xb0000
	s_waitcnt vmcnt(8)
	v_pk_fma_f32 v[126:127], v[126:127], v[160:161], v[170:171]
	v_pk_fma_f32 v[128:129], v[128:129], v[158:159], v[172:173]
	v_pk_fma_f32 v[122:123], v[122:123], v[156:157], v[174:175]
	v_pk_fma_f32 v[124:125], v[124:125], v[154:155], v[176:177]
	v_pk_fma_f32 v[118:119], v[118:119], v[152:153], v[178:179]
	v_pk_fma_f32 v[120:121], v[120:121], v[150:151], v[180:181]
	v_pk_fma_f32 v[114:115], v[114:115], v[148:149], v[182:183]
	v_pk_fma_f32 v[116:117], v[116:117], v[146:147], v[184:185]
	global_store_dwordx4 v[162:163], v[126:129], off
	global_store_dwordx4 v[162:163], v[122:125], off offset:16
	global_store_dwordx4 v[162:163], v[118:121], off offset:512
	global_store_dwordx4 v[162:163], v[114:117], off offset:528
	global_load_dwordx4 v[170:173], v[240:241], off
	global_load_dwordx4 v[174:177], v[240:241], off offset:16
	global_load_dwordx4 v[178:181], v[240:241], off offset:512
	global_load_dwordx4 v[182:185], v[240:241], off offset:528
	s_waitcnt vmcnt(12)
	v_pk_fma_f32 v[110:111], v[110:111], v[160:161], v[186:187]
	v_pk_fma_f32 v[112:113], v[112:113], v[158:159], v[188:189]
	v_pk_fma_f32 v[106:107], v[106:107], v[156:157], v[192:193]
	v_pk_fma_f32 v[108:109], v[108:109], v[154:155], v[194:195]
	v_pk_fma_f32 v[102:103], v[102:103], v[152:153], v[196:197]
	v_pk_fma_f32 v[104:105], v[104:105], v[150:151], v[198:199]
	v_pk_fma_f32 v[98:99], v[98:99], v[148:149], v[200:201]
	v_pk_fma_f32 v[100:101], v[100:101], v[146:147], v[202:203]
	global_store_dwordx4 v[164:165], v[110:113], off
	global_store_dwordx4 v[164:165], v[106:109], off offset:16
	global_store_dwordx4 v[164:165], v[102:105], off offset:512
	global_store_dwordx4 v[164:165], v[98:101], off offset:528
	global_load_dwordx4 v[186:189], v[242:243], off
	global_load_dwordx4 v[192:195], v[242:243], off offset:16
	global_load_dwordx4 v[196:199], v[242:243], off offset:512
	global_load_dwordx4 v[200:203], v[242:243], off offset:528
	s_waitcnt vmcnt(16)
	v_pk_fma_f32 v[94:95], v[94:95], v[160:161], v[218:219]
	v_pk_fma_f32 v[96:97], v[96:97], v[158:159], v[220:221]
	v_pk_fma_f32 v[90:91], v[90:91], v[156:157], v[222:223]
	v_pk_fma_f32 v[92:93], v[92:93], v[154:155], v[224:225]
	v_pk_fma_f32 v[86:87], v[86:87], v[152:153], v[230:231]
	v_pk_fma_f32 v[88:89], v[88:89], v[150:151], v[232:233]
	v_pk_fma_f32 v[82:83], v[82:83], v[148:149], v[234:235]
	v_pk_fma_f32 v[84:85], v[84:85], v[146:147], v[236:237]
	global_store_dwordx4 v[238:239], v[94:97], off
	global_store_dwordx4 v[238:239], v[90:93], off offset:16
	global_store_dwordx4 v[238:239], v[86:89], off offset:512
	global_store_dwordx4 v[238:239], v[82:85], off offset:528
	global_load_dwordx4 v[218:221], v[244:245], off
	global_load_dwordx4 v[222:225], v[244:245], off offset:16
	global_load_dwordx4 v[230:233], v[244:245], off offset:512
	global_load_dwordx4 v[234:237], v[244:245], off offset:528
	s_waitcnt vmcnt(16)
;     __device__ __forceinline__ void operator()(const pg8::f32x4 (&acc)[2][2][4][2], const pg8::Unit& uu, int wr, int wc, int fr, int fq) const {
;     ...
;         if (!((uu.pn >> 30) & 1)) {
; #pragma unroll
;             for (int ai = 0; ai < 2; ++ai)
; #pragma unroll
;                 for (int m = 0; m < 4; ++m) { float* rowp = base + (size_t)(wr * 64 + fr + ai * 128 + m * 16) * D + col0;
; #pragma unroll
;                     for (int bj = 0; bj < 2; ++bj)
; #pragma unroll
;                         for (int n = 0; n < 2; ++n) { pg8::f32x4* p = (pg8::f32x4*)(rowp + bj * 128 + 4 * n); *p = *p + gv[bj][n] * acc[ai][bj][m][n]; } }
	v_pk_fma_f32 v[78:79], v[78:79], v[160:161], v[170:171]
	v_pk_fma_f32 v[80:81], v[80:81], v[158:159], v[172:173]
	v_pk_fma_f32 v[74:75], v[74:75], v[156:157], v[174:175]
	v_pk_fma_f32 v[76:77], v[76:77], v[154:155], v[176:177]
	v_pk_fma_f32 v[70:71], v[70:71], v[152:153], v[178:179]
	v_pk_fma_f32 v[72:73], v[72:73], v[150:151], v[180:181]
	v_pk_fma_f32 v[66:67], v[66:67], v[148:149], v[182:183]
	v_pk_fma_f32 v[68:69], v[68:69], v[146:147], v[184:185]
	global_store_dwordx4 v[240:241], v[78:81], off
	global_store_dwordx4 v[240:241], v[74:77], off offset:16
	global_store_dwordx4 v[240:241], v[70:73], off offset:512
	global_store_dwordx4 v[240:241], v[66:69], off offset:528
	global_load_dwordx4 v[170:173], v[246:247], off
	global_load_dwordx4 v[174:177], v[246:247], off offset:16
	global_load_dwordx4 v[178:181], v[246:247], off offset:512
	global_load_dwordx4 v[182:185], v[246:247], off offset:528
	s_waitcnt vmcnt(16)
	v_pk_fma_f32 v[62:63], v[62:63], v[160:161], v[186:187]
	v_pk_fma_f32 v[64:65], v[64:65], v[158:159], v[188:189]
	v_pk_fma_f32 v[58:59], v[58:59], v[156:157], v[192:193]
	v_pk_fma_f32 v[60:61], v[60:61], v[154:155], v[194:195]
	v_pk_fma_f32 v[54:55], v[54:55], v[152:153], v[196:197]
	v_pk_fma_f32 v[56:57], v[56:57], v[150:151], v[198:199]
	v_pk_fma_f32 v[50:51], v[50:51], v[148:149], v[200:201]
	v_pk_fma_f32 v[52:53], v[52:53], v[146:147], v[202:203]
	global_store_dwordx4 v[242:243], v[62:65], off
	global_store_dwordx4 v[242:243], v[58:61], off offset:16
	global_store_dwordx4 v[242:243], v[54:57], off offset:512
	global_store_dwordx4 v[242:243], v[50:53], off offset:528
	global_load_dwordx4 v[186:189], v[248:249], off
	global_load_dwordx4 v[192:195], v[248:249], off offset:16
	global_load_dwordx4 v[196:199], v[248:249], off offset:512
	global_load_dwordx4 v[200:203], v[248:249], off offset:528
	s_waitcnt vmcnt(16)
	v_pk_fma_f32 v[46:47], v[46:47], v[160:161], v[218:219]
	v_pk_fma_f32 v[48:49], v[48:49], v[158:159], v[220:221]
	v_pk_fma_f32 v[42:43], v[42:43], v[156:157], v[222:223]
	v_pk_fma_f32 v[44:45], v[44:45], v[154:155], v[224:225]
	v_pk_fma_f32 v[38:39], v[38:39], v[152:153], v[230:231]
	v_pk_fma_f32 v[40:41], v[40:41], v[150:151], v[232:233]
	v_pk_fma_f32 v[34:35], v[34:35], v[148:149], v[234:235]
	v_pk_fma_f32 v[36:37], v[36:37], v[146:147], v[236:237]
	global_store_dwordx4 v[244:245], v[46:49], off
	global_store_dwordx4 v[244:245], v[42:45], off offset:16
	global_store_dwordx4 v[244:245], v[38:41], off offset:512
	global_store_dwordx4 v[244:245], v[34:37], off offset:528
	s_waitcnt vmcnt(12)
	v_pk_fma_f32 v[30:31], v[30:31], v[160:161], v[170:171]
	v_pk_fma_f32 v[32:33], v[32:33], v[158:159], v[172:173]
	v_pk_fma_f32 v[26:27], v[26:27], v[156:157], v[174:175]
	v_pk_fma_f32 v[28:29], v[28:29], v[154:155], v[176:177]
	v_pk_fma_f32 v[22:23], v[22:23], v[152:153], v[178:179]
	v_pk_fma_f32 v[24:25], v[24:25], v[150:151], v[180:181]
	v_pk_fma_f32 v[18:19], v[18:19], v[148:149], v[182:183]
	v_pk_fma_f32 v[20:21], v[20:21], v[146:147], v[184:185]
	global_store_dwordx4 v[246:247], v[30:33], off
	global_store_dwordx4 v[246:247], v[26:29], off offset:16
	global_store_dwordx4 v[246:247], v[22:25], off offset:512
	global_store_dwordx4 v[246:247], v[18:21], off offset:528
	s_waitcnt vmcnt(8)
	v_pk_fma_f32 v[14:15], v[14:15], v[160:161], v[186:187]
	v_pk_fma_f32 v[16:17], v[16:17], v[158:159], v[188:189]
	v_pk_fma_f32 v[10:11], v[10:11], v[156:157], v[192:193]
	v_pk_fma_f32 v[12:13], v[12:13], v[154:155], v[194:195]
	v_pk_fma_f32 v[6:7], v[6:7], v[152:153], v[196:197]
	v_pk_fma_f32 v[8:9], v[8:9], v[150:151], v[198:199]
	v_pk_fma_f32 v[2:3], v[2:3], v[148:149], v[200:201]
	v_pk_fma_f32 v[4:5], v[4:5], v[146:147], v[202:203]
	global_store_dwordx4 v[248:249], v[14:17], off
	global_store_dwordx4 v[248:249], v[10:13], off offset:16
	global_store_dwordx4 v[248:249], v[6:9], off offset:512
	global_store_dwordx4 v[248:249], v[2:5], off offset:528
	s_and_b64 vcc, exec, s[38:39]
	s_mov_b64 s[38:39], -1
	s_cbranch_vccnz .LBB0_48

; __device__ __forceinline__ void p0_phase(ArgP a, LAS unsigned char* lds, int tid, int wave, int lane, int bid, int G) {
;     const int gt = bid * NTHR + tid, GT = G * NTHR;
;     { const f32x4* xs = (const f32x4*)a->in[0]; f32x4* xd = (f32x4*)a->out;
;       for (int i = gt; i < MLAT * D / 4; i += GT) xd[i] = xs[i];
;       const f32x4* cs = (const f32x4*)a->in[2]; f32x4* cd = (f32x4*)(a->ws + OFF_HC);
;       for (int i = gt; i < NB * C * D / 4; i += GT) cd[i] = cs[i]; }
.LBB0_1091:
	s_and_b64 vcc, exec, s[0:1]
	s_cbranch_vccz .LBB0_1127
	v_mbcnt_lo_u32_b32 v2, -1, 0
	v_mbcnt_hi_u32_b32 v2, -1, v2
	s_mov_b32 s1, 0x800000
	v_lshl_add_u32 v4, s16, 6, v2
	v_lshl_add_u32 v6, s89, 9, v4
	s_lshl_b32 s0, s90, 9
	s_load_dwordx2 s[20:21], s[30:31], 0x0
	s_lshl_b32 s1, s89, 3
	s_add_i32 s1, s1, s16
	v_lshlrev_b32_e32 v8, 4, v2
	s_waitcnt lgkmcnt(0)
.Lp0_copy:
	s_cmp_ge_i32 s1, 0x4000
	s_cbranch_scc1 .Lp0_copy_done
	s_lshl_b32 s12, s1, 13
	s_add_u32 s14, s20, s12
	s_addc_u32 s15, s21, 0
	s_add_u32 s12, s8, s12
	s_addc_u32 s13, s9, 0
	global_load_dwordx4 v[16:19], v8, s[14:15]
	global_load_dwordx4 v[20:23], v8, s[14:15] offset:1024
	global_load_dwordx4 v[24:27], v8, s[14:15] offset:2048
	global_load_dwordx4 v[28:31], v8, s[14:15] offset:3072
	s_add_u32 s14, s14, 0x1000
	s_addc_u32 s15, s15, 0
	global_load_dwordx4 v[32:35], v8, s[14:15]
	global_load_dwordx4 v[36:39], v8, s[14:15] offset:1024
	global_load_dwordx4 v[40:43], v8, s[14:15] offset:2048
	global_load_dwordx4 v[44:47], v8, s[14:15] offset:3072
	s_waitcnt vmcnt(7)
	global_store_dwordx4 v8, v[16:19], s[12:13]
	s_waitcnt vmcnt(7)
	global_store_dwordx4 v8, v[20:23], s[12:13] offset:1024
	s_waitcnt vmcnt(7)
	global_store_dwordx4 v8, v[24:27], s[12:13] offset:2048
	s_waitcnt vmcnt(7)
	global_store_dwordx4 v8, v[28:31], s[12:13] offset:3072
	s_add_u32 s12, s12, 0x1000
	s_addc_u32 s13, s13, 0
	s_waitcnt vmcnt(7)
	global_store_dwordx4 v8, v[32:35], s[12:13]
	s_waitcnt vmcnt(7)
	global_store_dwordx4 v8, v[36:39], s[12:13] offset:1024
	s_waitcnt vmcnt(7)
	global_store_dwordx4 v8, v[40:43], s[12:13] offset:2048
	s_waitcnt vmcnt(7)
	global_store_dwordx4 v8, v[44:47], s[12:13] offset:3072
	s_lshl_b32 s14, s90, 3
	s_add_i32 s1, s1, s14
	s_branch .Lp0_copy
.Lp0_copy_done:
.LBB0_1095:
	s_mov_b32 s1, 0x40000
	v_cmp_gt_i32_e32 vcc, s1, v6
	s_and_saveexec_b64 s[2:3], vcc
	s_cbranch_execz .LBB0_1098
	v_ashrrev_i32_e32 v7, 31, v6
	s_ashr_i32 s1, s0, 31
	v_lshlrev_b64 v[8:9], 4, v[6:7]
	s_lshl_b64 s[8:9], s[0:1], 4
	s_mov_b64 s[12:13], 0

; __device__ __forceinline__ void xcd_barrier(const XcdBarrier& b, int tid) {
;     asm volatile("s_waitcnt vmcnt(0)" ::: "memory");
;     __syncthreads();
;     if (tid == 0) {
;         unsigned* bar = b.bar;
;         __builtin_amdgcn_s_waitcnt(0);
;         unsigned nloc = b.st[0], nx = b.st[1];
;         if (nloc == 0u) { xcd_barrier_complete(bar, b.x, nloc, nx); b.st[0] = nloc; b.st[1] = nx; }
; __global__ void __launch_bounds__(NTHR) fwd_megakernel(Args a_unused) {
;     ...
;         if (ph + 1 < ph_hi) { if (ph == 0) grid.sync(); else { int l2; asm volatile("v_mbcnt_lo_u32_b32 %0, -1, 0\n\tv_mbcnt_hi_u32_b32 %0, -1, %0" : "=v"(l2)); xcd_barrier(xbar, wave0 * 64 + l2); } }
.LBB0_1127:
	s_add_i32 s42, s42, 1
	s_cmp_ge_i32 s42, s43
	s_mov_b64 s[0:1], -1
	s_cbranch_scc1 .LBB0_10
	v_readlane_b32 s0, v254, 41
	v_readlane_b32 s1, v254, 42
	s_and_b64 vcc, exec, s[0:1]
	v_mbcnt_lo_u32_b32 v1, -1, 0
	v_mbcnt_hi_u32_b32 v1, -1, v1
	s_waitcnt vmcnt(0)
	v_readlane_b32 s0, v253, 8
	v_sub_u32_e32 v1, 0, v1
	s_waitcnt vmcnt(0) lgkmcnt(0)
	v_cmp_eq_u32_e32 vcc, s0, v1
	s_barrier
	s_and_saveexec_b64 s[0:1], vcc
	s_cbranch_execz .LBB0_1182
	v_readlane_b32 s2, v254, 36
	s_waitcnt vmcnt(0) expcnt(0) lgkmcnt(0)
	s_nop 0
	v_mov_b32_e32 v1, s2
	ds_read_b32 v3, v1
	v_readlane_b32 s2, v254, 37
	s_waitcnt lgkmcnt(0)
	v_cmp_ne_u32_e32 vcc, 0, v3
	v_mov_b32_e32 v1, s2
	ds_read_b32 v2, v1
	s_cbranch_vccnz .LBB0_1146
	s_mov_b32 s12, 1
	s_branch .LBB0_1133
